# hgrn_b3: pass-1, state and V-column global loads hoisted to the top of the item (one round trip)
# speedup vs baseline: 1.0296x; 1.0044x over previous
.LBB0_1585:
	s_ashr_i32 s22, s40, 8
	s_ashr_i32 s23, s22, 31
	v_mov_b32_e32 v25, v220
	s_lshl_b64 s[54:55], s[22:23], 12
	s_and_b32 s22, s17, 0xfc0
	s_or_b32 s54, s54, s22
	v_readfirstlane_b32 s44, v25
	s_ashr_i32 s43, s44, 6
	s_lshl_b64 s[22:23], s[54:55], 11
	s_add_u32 s22, s8, s22
	s_addc_u32 s23, s9, s23
	s_and_b32 s42, s1, 0x180
	s_lshl_b32 s35, s42, 2
	v_and_b32_e32 v8, 15, v25
	s_add_u32 s22, s22, s35
	v_ashrrev_i32_e32 v26, 4, v25
	s_addc_u32 s23, s23, 0
	v_lshlrev_b32_e32 v96, 5, v8
	v_ashrrev_i32_e32 v27, 31, v26
	v_lshlrev_b32_e32 v20, 3, v8
	v_lshl_add_u64 v[0:1], s[22:23], 0, v[96:97]
	s_mov_b64 s[22:23], 0xf800
	v_lshlrev_b32_e32 v28, 4, v8
	v_lshl_add_u64 v[8:9], s[54:55], 0, v[26:27]
	v_lshl_add_u64 v[2:3], v[0:1], 0, s[22:23]
	s_mov_b32 s22, 0xf000
	v_lshlrev_b64 v[16:17], 9, v[8:9]
	v_add_co_u32_e32 v0, vcc, s22, v0
	v_or3_b32 v16, v16, v20, s42
	s_nop 0
	v_addc_co_u32_e32 v1, vcc, 0, v1, vcc
	v_lshl_add_u64 v[12:13], v[16:17], 2, s[8:9]
	flat_load_dwordx4 v[4:7], v[0:1] offset:2048
	s_nop 0
	global_load_dwordx4 v[0:3], v[2:3], off offset:16
	s_nop 0
	global_load_dwordx4 v[8:11], v[12:13], off offset:16
	s_nop 0
	global_load_dwordx4 v[12:15], v[12:13], off
	v_lshlrev_b64 v[16:17], 1, v[16:17]
	v_lshl_add_u64 v[18:19], s[10:11], 0, v[16:17]
	global_load_dwordx4 v[30:33], v[18:19], off
	v_lshl_add_u64 v[16:17], s[24:25], 0, v[16:17]
	global_load_dwordx4 v[16:19], v[16:17], off
	s_movk_i32 s35, 0x110
	v_add_u32_e32 v24, 0, v28
	v_mul_lo_u32 v29, v26, s35
	v_add_u32_e32 v27, v24, v29
	v_add_u32_e32 v29, 0x2200, v29
	s_lshl_b32 s48, s42, 1
	s_mov_b64 s[58:59], -1
	s_cmp_gt_i32 s43, 2
	v_add_u32_e32 v148, 32, v26
	v_mov_b32_e32 v149, 0
	v_lshl_add_u64 v[148:149], s[54:55], 0, v[148:149]
	v_lshlrev_b64 v[150:151], 9, v[148:149]
	v_or3_b32 v150, v150, v20, s42
	v_lshlrev_b64 v[152:153], 1, v[150:151]
	v_lshl_add_u64 v[154:155], v[150:151], 2, s[8:9]
	global_load_dwordx4 v[116:119], v[154:155], off offset:16
	global_load_dwordx4 v[120:123], v[154:155], off
	v_lshl_add_u64 v[156:157], s[10:11], 0, v[152:153]
	global_load_dwordx4 v[124:127], v[156:157], off
	v_lshl_add_u64 v[156:157], s[24:25], 0, v[152:153]
	global_load_dwordx4 v[128:131], v[156:157], off
	v_mov_b32_e32 v159, 0
	v_lshl_or_b32 v158, v26, 8, v28
	v_lshl_add_u64 v[160:161], s[14:15], 0, v[158:159]
	global_load_dwordx4 v[100:103], v[160:161], off
	v_add_u32_e32 v158, 32, v26
	v_lshl_or_b32 v158, v158, 8, v28
	v_lshl_add_u64 v[160:161], s[14:15], 0, v[158:159]
	global_load_dwordx4 v[104:107], v[160:161], off
	v_add_u32_e32 v158, 64, v26
	v_lshl_or_b32 v158, v158, 8, v28
	v_lshl_add_u64 v[160:161], s[14:15], 0, v[158:159]
	global_load_dwordx4 v[108:111], v[160:161], off
	v_add_u32_e32 v158, 96, v26
	v_lshl_or_b32 v158, v158, 8, v28
	v_lshl_add_u64 v[160:161], s[14:15], 0, v[158:159]
	global_load_dwordx4 v[112:115], v[160:161], off
	v_ashrrev_i32_e32 v162, 3, v25
	v_and_b32_e32 v162, -16, v162
	v_mov_b32_e32 v163, 0
	v_lshl_add_u64 v[162:163], s[54:55], 0, v[162:163]
	v_lshlrev_b64 v[162:163], 10, v[162:163]
	v_lshl_add_u64 v[162:163], s[30:31], 0, v[162:163]
	v_lshl_add_u64 v[162:163], v[162:163], 0, s[48:49]
	v_and_b32_e32 v164, 0x7f, v25
	v_lshlrev_b32_e32 v164, 1, v164
	v_mov_b32_e32 v165, 0
	v_lshl_add_u64 v[162:163], v[162:163], 0, v[164:165]
	v_lshl_add_u64 v[166:167], s[62:63], 4, v[162:163]
	v_lshl_add_u64 v[168:169], s[62:63], 4, v[166:167]
	v_lshl_add_u64 v[170:171], s[62:63], 4, v[168:169]
	global_load_ushort v132, v[162:163], off
	global_load_ushort v133, v[162:163], off offset:1024
	global_load_ushort v134, v[162:163], off offset:2048
	global_load_ushort v135, v[162:163], off offset:3072
	global_load_ushort v136, v[166:167], off
	global_load_ushort v137, v[166:167], off offset:1024
	global_load_ushort v138, v[166:167], off offset:2048
	global_load_ushort v139, v[166:167], off offset:3072
	global_load_ushort v140, v[168:169], off
	global_load_ushort v141, v[168:169], off offset:1024
	global_load_ushort v142, v[168:169], off offset:2048
	global_load_ushort v143, v[168:169], off offset:3072
	global_load_ushort v144, v[170:171], off
	global_load_ushort v145, v[170:171], off offset:1024
	global_load_ushort v146, v[170:171], off offset:2048
	global_load_ushort v147, v[170:171], off offset:3072
	s_waitcnt vmcnt(0)
	v_mul_f32_e32 v21, 0x3fb8aa3b, v12
	v_exp_f32_e32 v22, v21
	v_mul_f32_e32 v21, 0x3fb8aa3b, v13
	v_exp_f32_e32 v23, v21
	v_lshlrev_b32_e32 v34, 16, v30
	v_and_b32_e32 v35, 0xffff0000, v30
	v_mul_f32_e32 v21, 0x3fb8aa3b, v14
	v_pk_mul_f32 v[22:23], v[22:23], v[34:35]
	v_exp_f32_e32 v34, v21
	v_mul_f32_e32 v21, 0x3fb8aa3b, v15
	v_exp_f32_e32 v35, v21
	v_lshlrev_b32_e32 v30, 16, v31
	v_and_b32_e32 v31, 0xffff0000, v31
	v_mul_f32_e32 v21, 0x3fb8aa3b, v8
	v_pk_mul_f32 v[34:35], v[34:35], v[30:31]
	v_exp_f32_e32 v30, v21
	v_mul_f32_e32 v21, 0x3fb8aa3b, v9
	v_exp_f32_e32 v31, v21
	v_lshlrev_b32_e32 v36, 16, v32
	v_and_b32_e32 v37, 0xffff0000, v32
	v_mul_f32_e32 v21, 0x3fb8aa3b, v10
	v_pk_mul_f32 v[36:37], v[30:31], v[36:37]
	v_exp_f32_e32 v30, v21
	v_mul_f32_e32 v21, 0x3fb8aa3b, v11
	v_exp_f32_e32 v31, v21
	v_max_f32_e64 v21, -v12, -v12
	v_min_f32_e32 v21, 0x42a00000, v21
	v_lshlrev_b32_e32 v32, 16, v33
	v_and_b32_e32 v33, 0xffff0000, v33
	v_mul_f32_e32 v21, 0x3fb8aa3b, v21
	v_pk_mul_f32 v[38:39], v[30:31], v[32:33]
	v_cvt_pk_bf16_f32 v30, v22, v23
	v_exp_f32_e32 v22, v21
	v_max_f32_e64 v21, -v13, -v13
	s_waitcnt lgkmcnt(0)
	v_sub_f32_e32 v12, v4, v12
	v_min_f32_e32 v21, 0x42a00000, v21
	v_sub_f32_e32 v13, v5, v13
	v_mul_f32_e32 v12, 0x3fb8aa3b, v12
	v_mul_f32_e32 v21, 0x3fb8aa3b, v21
	v_mul_f32_e32 v13, 0x3fb8aa3b, v13
	v_cvt_pk_bf16_f32 v31, v34, v35
	v_cvt_pk_bf16_f32 v32, v36, v37
	v_cvt_pk_bf16_f32 v33, v38, v39
	v_exp_f32_e32 v12, v12
	v_exp_f32_e32 v23, v21
	v_exp_f32_e32 v13, v13
	ds_write_b128 v27, v[30:33]
	v_lshlrev_b32_e32 v30, 16, v16
	v_and_b32_e32 v31, 0xffff0000, v16
	v_max_f32_e64 v16, -v14, -v14
	v_min_f32_e32 v16, 0x42a00000, v16
	v_mul_f32_e32 v16, 0x3fb8aa3b, v16
	v_pk_mul_f32 v[12:13], v[12:13], v[30:31]
	v_pk_mul_f32 v[22:23], v[22:23], v[30:31]
	v_exp_f32_e32 v30, v16
	v_max_f32_e64 v16, -v15, -v15
	v_sub_f32_e32 v14, v6, v14
	v_min_f32_e32 v16, 0x42a00000, v16
	v_sub_f32_e32 v15, v7, v15
	v_mul_f32_e32 v14, 0x3fb8aa3b, v14
	v_mul_f32_e32 v16, 0x3fb8aa3b, v16
	v_mul_f32_e32 v15, 0x3fb8aa3b, v15
	v_exp_f32_e32 v14, v14
	v_exp_f32_e32 v31, v16
	v_exp_f32_e32 v15, v15
	v_max_f32_e64 v21, -v8, -v8
	v_min_f32_e32 v21, 0x42a00000, v21
	v_lshlrev_b32_e32 v16, 16, v17
	v_and_b32_e32 v17, 0xffff0000, v17
	v_mul_f32_e32 v21, 0x3fb8aa3b, v21
	v_pk_mul_f32 v[14:15], v[14:15], v[16:17]
	v_pk_mul_f32 v[16:17], v[30:31], v[16:17]
	v_exp_f32_e32 v30, v21
	v_sub_f32_e32 v8, v0, v8
	v_max_f32_e64 v21, -v9, -v9
	v_sub_f32_e32 v9, v1, v9
	v_mul_f32_e32 v8, 0x3fb8aa3b, v8
	v_mul_f32_e32 v9, 0x3fb8aa3b, v9
	v_exp_f32_e32 v8, v8
	v_exp_f32_e32 v9, v9
	v_lshlrev_b32_e32 v32, 16, v18
	v_and_b32_e32 v33, 0xffff0000, v18
	v_min_f32_e32 v21, 0x42a00000, v21
	v_pk_mul_f32 v[34:35], v[8:9], v[32:33]
	v_sub_f32_e32 v9, v2, v10
	v_mul_f32_e32 v9, 0x3fb8aa3b, v9
	v_max_f32_e64 v8, -v10, -v10
	v_exp_f32_e32 v10, v9
	v_max_f32_e64 v9, -v11, -v11
	v_min_f32_e32 v8, 0x42a00000, v8
	v_min_f32_e32 v9, 0x42a00000, v9
	v_sub_f32_e32 v11, v3, v11
	v_mul_f32_e32 v21, 0x3fb8aa3b, v21
	v_mul_f32_e32 v8, 0x3fb8aa3b, v8
	v_mul_f32_e32 v9, 0x3fb8aa3b, v9
	v_mul_f32_e32 v11, 0x3fb8aa3b, v11
	v_exp_f32_e32 v31, v21
	v_exp_f32_e32 v8, v8
	v_exp_f32_e32 v9, v9
	v_exp_f32_e32 v11, v11
	v_lshlrev_b32_e32 v18, 16, v19
	v_and_b32_e32 v19, 0xffff0000, v19
	v_pk_mul_f32 v[30:31], v[30:31], v[32:33]
	v_pk_mul_f32 v[32:33], v[10:11], v[18:19]
	v_pk_mul_f32 v[18:19], v[8:9], v[18:19]
	v_cvt_pk_bf16_f32 v8, v22, v23
	v_cvt_pk_bf16_f32 v9, v16, v17
	v_cvt_pk_bf16_f32 v10, v30, v31
	v_cvt_pk_bf16_f32 v11, v18, v19
	ds_write_b128 v27, v[8:11] offset:26112
	v_cvt_pk_bf16_f32 v8, v12, v13
	v_cvt_pk_bf16_f32 v9, v14, v15
	v_cvt_pk_bf16_f32 v10, v34, v35
	v_cvt_pk_bf16_f32 v11, v32, v33
	ds_write_b128 v27, v[8:11] offset:34816
	v_add_u32_e32 v8, 32, v26
	v_ashrrev_i32_e32 v9, 31, v8
	v_lshl_add_u64 v[8:9], s[54:55], 0, v[8:9]
	v_lshlrev_b64 v[16:17], 9, v[8:9]
	v_or3_b32 v16, v16, v20, s42
	v_lshlrev_b64 v[20:21], 1, v[16:17]
	v_lshl_add_u64 v[12:13], v[16:17], 2, s[8:9]
	v_lshl_add_u64 v[16:17], s[10:11], 0, v[20:21]
	v_mov_b32_e32 v8, v116
	v_mov_b32_e32 v9, v117
	v_mov_b32_e32 v10, v118
	v_mov_b32_e32 v11, v119
	s_nop 0
	v_mov_b32_e32 v12, v120
	v_mov_b32_e32 v13, v121
	v_mov_b32_e32 v14, v122
	v_mov_b32_e32 v15, v123
	v_lshl_add_u64 v[20:21], s[24:25], 0, v[20:21]
	v_mov_b32_e32 v16, v124
	v_mov_b32_e32 v17, v125
	v_mov_b32_e32 v18, v126
	v_mov_b32_e32 v19, v127
	s_waitcnt vmcnt(1)
	v_mul_f32_e32 v30, 0x3fb8aa3b, v12
	v_mov_b32_e32 v20, v128
	v_mov_b32_e32 v21, v129
	v_mov_b32_e32 v22, v130
	v_mov_b32_e32 v23, v131
	s_waitcnt vmcnt(1)
	v_lshlrev_b32_e32 v32, 16, v16
	v_and_b32_e32 v33, 0xffff0000, v16
	v_mul_f32_e32 v16, 0x3fb8aa3b, v14
	v_exp_f32_e32 v34, v16
	v_mul_f32_e32 v16, 0x3fb8aa3b, v15
	v_exp_f32_e32 v35, v16
	v_lshlrev_b32_e32 v36, 16, v17
	v_and_b32_e32 v37, 0xffff0000, v17
	v_mul_f32_e32 v16, 0x3fb8aa3b, v8
	v_mul_f32_e32 v17, 0x3fb8aa3b, v9
	v_exp_f32_e32 v16, v16
	v_exp_f32_e32 v17, v17
	v_lshlrev_b32_e32 v38, 16, v18
	v_and_b32_e32 v39, 0xffff0000, v18
	v_mul_f32_e32 v31, 0x3fb8aa3b, v13
	v_pk_mul_f32 v[40:41], v[16:17], v[38:39]
	v_mul_f32_e32 v16, 0x3fb8aa3b, v10
	v_mul_f32_e32 v17, 0x3fb8aa3b, v11
	v_exp_f32_e32 v30, v30
	v_exp_f32_e32 v31, v31
	v_exp_f32_e32 v16, v16
	v_exp_f32_e32 v17, v17
	v_lshlrev_b32_e32 v42, 16, v19
	v_and_b32_e32 v43, 0xffff0000, v19
	v_pk_mul_f32 v[30:31], v[30:31], v[32:33]
	v_pk_mul_f32 v[34:35], v[34:35], v[36:37]
	v_pk_mul_f32 v[44:45], v[16:17], v[42:43]
	v_cvt_pk_bf16_f32 v16, v30, v31
	v_cvt_pk_bf16_f32 v17, v34, v35
	v_cvt_pk_bf16_f32 v18, v40, v41
	v_cvt_pk_bf16_f32 v19, v44, v45
	v_add_u32_e32 v30, v24, v29
	ds_write_b128 v30, v[16:19]
	v_sub_f32_e32 v16, v12, v4
	v_sub_f32_e32 v4, v4, v12
	v_sub_f32_e32 v12, v13, v5
	v_sub_f32_e32 v5, v5, v13
	v_min_f32_e32 v4, 0x42a00000, v4
	v_min_f32_e32 v5, 0x42a00000, v5
	v_mul_f32_e32 v4, 0x3fb8aa3b, v4
	v_mul_f32_e32 v5, 0x3fb8aa3b, v5
	v_exp_f32_e32 v4, v4
	v_exp_f32_e32 v5, v5
	v_mul_f32_e32 v12, 0x3fb8aa3b, v12
	v_exp_f32_e32 v17, v12
	v_mul_f32_e32 v16, 0x3fb8aa3b, v16
	v_exp_f32_e32 v16, v16
	s_waitcnt vmcnt(0)
	v_lshlrev_b32_e32 v12, 16, v20
	v_and_b32_e32 v13, 0xffff0000, v20
	v_pk_mul_f32 v[4:5], v[4:5], v[12:13]
	v_sub_f32_e32 v12, v14, v6
	v_sub_f32_e32 v6, v6, v14
	v_sub_f32_e32 v13, v15, v7
	v_sub_f32_e32 v7, v7, v15
	v_min_f32_e32 v6, 0x42a00000, v6
	v_min_f32_e32 v7, 0x42a00000, v7
	v_mul_f32_e32 v6, 0x3fb8aa3b, v6
	v_mul_f32_e32 v7, 0x3fb8aa3b, v7
	v_exp_f32_e32 v6, v6
	v_exp_f32_e32 v7, v7
	v_lshlrev_b32_e32 v14, 16, v21
	v_and_b32_e32 v15, 0xffff0000, v21
	v_mul_f32_e32 v12, 0x3fb8aa3b, v12
	v_pk_mul_f32 v[6:7], v[6:7], v[14:15]
	v_sub_f32_e32 v14, v8, v0
	v_sub_f32_e32 v0, v0, v8
	v_sub_f32_e32 v8, v9, v1
	v_sub_f32_e32 v1, v1, v9
	v_min_f32_e32 v0, 0x42a00000, v0
	v_min_f32_e32 v1, 0x42a00000, v1
	v_mul_f32_e32 v0, 0x3fb8aa3b, v0
	v_mul_f32_e32 v1, 0x3fb8aa3b, v1
	v_exp_f32_e32 v0, v0
	v_exp_f32_e32 v1, v1
	v_mul_f32_e32 v8, 0x3fb8aa3b, v8
	v_exp_f32_e32 v15, v8
	v_lshlrev_b32_e32 v8, 16, v22
	v_and_b32_e32 v9, 0xffff0000, v22
	v_pk_mul_f32 v[8:9], v[0:1], v[8:9]
	v_sub_f32_e32 v1, v2, v10
	v_min_f32_e32 v1, 0x42a00000, v1
	v_mul_f32_e32 v1, 0x3fb8aa3b, v1
	v_sub_f32_e32 v0, v10, v2
	v_exp_f32_e32 v2, v1
	v_sub_f32_e32 v1, v11, v3
	v_mul_f32_e32 v0, 0x3fb8aa3b, v0
	v_mul_f32_e32 v1, 0x3fb8aa3b, v1
	v_exp_f32_e32 v0, v0
	v_exp_f32_e32 v1, v1
	v_mul_f32_e32 v13, 0x3fb8aa3b, v13
	v_mul_f32_e32 v14, 0x3fb8aa3b, v14
	v_exp_f32_e32 v12, v12
	v_pk_mul_f32 v[18:19], v[0:1], v[42:43]
	v_sub_f32_e32 v0, v3, v11
	v_min_f32_e32 v0, 0x42a00000, v0
	v_exp_f32_e32 v13, v13
	v_exp_f32_e32 v14, v14
	v_mul_f32_e32 v0, 0x3fb8aa3b, v0
	v_exp_f32_e32 v3, v0
	v_pk_mul_f32 v[16:17], v[16:17], v[32:33]
	v_pk_mul_f32 v[12:13], v[12:13], v[36:37]
	v_pk_mul_f32 v[14:15], v[14:15], v[38:39]
	v_lshlrev_b32_e32 v0, 16, v23
	v_and_b32_e32 v1, 0xffff0000, v23
	v_pk_mul_f32 v[10:11], v[2:3], v[0:1]
	v_cvt_pk_bf16_f32 v0, v16, v17
	v_cvt_pk_bf16_f32 v1, v12, v13
	v_cvt_pk_bf16_f32 v2, v14, v15
	v_cvt_pk_bf16_f32 v3, v18, v19
	v_add3_u32 v12, 0, v29, v28
	ds_write_b128 v12, v[0:3] offset:8704
	v_cvt_pk_bf16_f32 v0, v4, v5
	v_cvt_pk_bf16_f32 v1, v6, v7
	v_cvt_pk_bf16_f32 v2, v8, v9
	v_cvt_pk_bf16_f32 v3, v10, v11
	ds_write_b128 v30, v[0:3] offset:34816
	v_lshlrev_b32_e32 v0, 7, v26
	v_ashrrev_i32_e32 v1, 31, v0
	v_lshlrev_b64 v[0:1], 1, v[0:1]
	v_or_b32_e32 v0, v0, v28
	v_lshl_add_u64 v[0:1], s[14:15], 0, v[0:1]
	v_ashrrev_i32_e32 v16, 3, v25
	v_and_b32_e32 v6, 0x7f, v25
	v_lshlrev_b32_e32 v96, 1, v6
	v_and_b32_e32 v17, 31, v25
	v_bfe_u32 v18, v25, 5, 1
	s_waitcnt vmcnt(0)
	ds_write_b128 v27, v[100:103] offset:52224
	v_add_u32_e32 v0, 0x200, v25
	v_ashrrev_i32_e32 v4, 4, v0
	v_lshlrev_b32_e32 v0, 7, v4
	v_ashrrev_i32_e32 v1, 31, v0
	v_lshlrev_b64 v[0:1], 1, v[0:1]
	v_or_b32_e32 v0, v0, v28
	v_lshl_add_u64 v[0:1], s[14:15], 0, v[0:1]
	v_mad_u64_u32 v[4:5], s[22:23], v4, s35, v[24:25]
	s_waitcnt vmcnt(0)
	ds_write_b128 v4, v[104:107] offset:52224
	v_add_u32_e32 v0, 0x400, v25
	v_ashrrev_i32_e32 v4, 4, v0
	v_lshlrev_b32_e32 v0, 7, v4
	v_ashrrev_i32_e32 v1, 31, v0
	v_lshlrev_b64 v[0:1], 1, v[0:1]
	v_or_b32_e32 v0, v0, v28
	v_lshl_add_u64 v[0:1], s[14:15], 0, v[0:1]
	v_mad_u64_u32 v[4:5], s[22:23], v4, s35, v[24:25]
	s_waitcnt vmcnt(0)
	ds_write_b128 v4, v[108:111] offset:52224
	v_add_u32_e32 v0, 0x600, v25
	v_ashrrev_i32_e32 v4, 4, v0
	v_lshlrev_b32_e32 v0, 7, v4
	v_ashrrev_i32_e32 v1, 31, v0
	v_lshlrev_b64 v[0:1], 1, v[0:1]
	v_or_b32_e32 v0, v0, v28
	v_lshl_add_u64 v[0:1], s[14:15], 0, v[0:1]
	v_mad_u64_u32 v[4:5], s[22:23], v4, s35, v[24:25]
	v_readlane_b32 s22, v249, 26
	s_waitcnt vmcnt(0)
	ds_write_b128 v4, v[112:115] offset:52224
	v_and_b32_e32 v0, -16, v16
	v_ashrrev_i32_e32 v1, 31, v0
	v_lshl_add_u64 v[2:3], s[54:55], 0, v[0:1]
	v_lshlrev_b64 v[2:3], 10, v[2:3]
	v_lshl_add_u64 v[2:3], s[30:31], 0, v[2:3]
	v_lshl_add_u64 v[2:3], v[2:3], 0, s[48:49]
	v_mov_b32_e32 v1, s22
	s_movk_i32 s22, 0x90
	v_lshl_add_u64 v[4:5], v[2:3], 0, v[96:97]
	v_mad_u32_u24 v8, v6, s22, v1
	v_lshl_add_u32 v10, v0, 1, v8
	v_add_co_u32_e32 v0, vcc, s67, v4
	s_movk_i32 s22, 0x3000
	v_perm_b32 v172, v133, v132, s47
	v_perm_b32 v173, v135, v134, s47
	v_perm_b32 v174, v137, v136, s47
	v_perm_b32 v175, v139, v138, s47
	v_perm_b32 v176, v141, v140, s47
	v_perm_b32 v177, v143, v142, s47
	v_perm_b32 v178, v145, v144, s47
	v_perm_b32 v179, v147, v146, s47
	ds_write_b128 v10, v[172:175]
	ds_write_b128 v10, v[176:179] offset:16
	s_waitcnt lgkmcnt(0)
	s_barrier
	s_cbranch_scc0 .LBB0_1589
	s_cmp_lg_u32 s43, 3
	s_cbranch_scc1 .LBB0_1588
	v_lshlrev_b32_e32 v0, 1, v17
	v_mul_u32_u24_e32 v1, 0x240, v18
	v_readlane_b32 s22, v249, 27
	s_nop 1
	v_add3_u32 v0, s22, v0, v1
	ds_write_b16 v0, v97 offset:64
	ds_write_b16 v0, v97 offset:208
	ds_write_b16 v0, v97 offset:352
	ds_write_b16 v0, v97 offset:496
	ds_write_b16 v0, v97 offset:1216
	ds_write_b16 v0, v97 offset:1360
	ds_write_b16 v0, v97 offset:1504
	ds_write_b16 v0, v97 offset:1648
	ds_write_b16 v0, v97 offset:2368
	ds_write_b16 v0, v97 offset:2512
	ds_write_b16 v0, v97 offset:2656
	ds_write_b16 v0, v97 offset:2800
	ds_write_b16 v0, v97 offset:3520
	ds_write_b16 v0, v97 offset:3664
	ds_write_b16 v0, v97 offset:3808
	ds_write_b16 v0, v97 offset:3952
